# k29 + MLA in-proj k_pe rope epilogue: both rope-table load pairs of a block issued together
# baseline (speedup 1.0000x reference)
.LBB0_492:
	s_andn2_saveexec_b64 s[30:31], s[30:31]
	s_cbranch_execz .LBB0_512
	s_and_saveexec_b64 vcc, s[48:49]
	s_cbranch_execz .LBB0_495
	v_or_b32_e32 v140, v181, v182
	v_lshlrev_b32_e32 v140, 7, v140
	v_mov_b32_e32 v141, v177
	v_lshl_add_u64 v[150:151], v[138:139], 0, v[140:141]
	v_lshl_add_u64 v[152:153], v[136:137], 0, v[140:141]
	global_load_dwordx4 v[142:145], v[150:151], off
	global_load_dwordx4 v[146:149], v[152:153], off
	global_load_dwordx4 v[228:231], v[150:151], off offset:64
	global_load_dwordx4 v[232:235], v[152:153], off offset:64
	s_waitcnt vmcnt(2)
	v_pk_mul_f32 v[154:155], v[124:125], v[146:147]
	v_pk_mul_f32 v[140:141], v[116:117], v[146:147]
	v_mul_f32_e32 v146, v126, v144
	v_mul_f32_e32 v156, v118, v148
	v_mul_f32_e32 v158, v126, v148
	v_mul_f32_e32 v144, v118, v144
	v_mov_b32_e32 v118, v127
	v_mov_b32_e32 v148, v145
	v_mov_b32_e32 v126, v119
	v_pk_mul_f32 v[160:161], v[118:119], v[148:149]
	v_pk_mul_f32 v[118:119], v[126:127], v[148:149]
	v_mov_b32_e32 v147, v160
	v_mov_b32_e32 v157, v161
	v_mov_b32_e32 v145, v118
	v_mov_b32_e32 v159, v119
	v_pk_fma_f32 v[124:125], v[124:125], v[142:143], v[140:141] neg_lo:[0,0,1] neg_hi:[0,0,1]
	v_pk_add_f32 v[140:141], v[146:147], v[156:157] neg_lo:[0,1] neg_hi:[0,1]
	v_pk_fma_f32 v[116:117], v[116:117], v[142:143], v[154:155]
	v_pk_add_f32 v[118:119], v[144:145], v[158:159]
	s_waitcnt vmcnt(1)
	v_mul_f32_e32 v150, v122, v230
	s_waitcnt vmcnt(0)
	v_mul_f32_e32 v152, v114, v234
	v_mul_f32_e32 v154, v122, v234
	v_mul_f32_e32 v230, v114, v230
	v_mov_b32_e32 v114, v123
	v_mov_b32_e32 v234, v231
	v_pk_mul_f32 v[156:157], v[114:115], v[234:235]
	v_mov_b32_e32 v122, v115
	v_pk_mul_f32 v[126:127], v[120:121], v[232:233]
	v_pk_mul_f32 v[232:233], v[112:113], v[232:233]
	v_mov_b32_e32 v151, v156
	v_mov_b32_e32 v153, v157
	v_pk_mul_f32 v[114:115], v[122:123], v[234:235]
	v_pk_fma_f32 v[120:121], v[120:121], v[228:229], v[232:233] neg_lo:[0,0,1] neg_hi:[0,0,1]
	v_pk_add_f32 v[232:233], v[150:151], v[152:153] neg_lo:[0,1] neg_hi:[0,1]
	v_mov_b32_e32 v231, v114
	v_mov_b32_e32 v155, v115
	v_pk_fma_f32 v[112:113], v[112:113], v[228:229], v[126:127]
	v_pk_add_f32 v[114:115], v[230:231], v[154:155]
	v_mov_b32_e32 v122, v232
	v_mov_b32_e32 v123, v233
	v_mov_b32_e32 v126, v140
	v_mov_b32_e32 v127, v141

.LBB0_528:
	s_andn2_saveexec_b64 s[30:31], s[30:31]
	s_cbranch_execz .LBB0_548
	s_and_saveexec_b64 vcc, s[48:49]
	s_cbranch_execz .LBB0_531
	v_or_b32_e32 v112, v181, v116
	v_lshlrev_b32_e32 v112, 7, v112
	v_mov_b32_e32 v113, v177
	v_lshl_add_u64 v[122:123], v[138:139], 0, v[112:113]
	v_lshl_add_u64 v[124:125], v[136:137], 0, v[112:113]
	global_load_dwordx4 v[118:121], v[122:123], off
	global_load_dwordx4 v[112:115], v[124:125], off
	global_load_dwordx4 v[228:231], v[122:123], off offset:64
	global_load_dwordx4 v[232:235], v[124:125], off offset:64
	s_waitcnt vmcnt(3)
	v_mul_f32_e32 v140, v110, v120
	s_waitcnt vmcnt(2)
	v_mul_f32_e32 v142, v102, v114
	v_mul_f32_e32 v144, v110, v114
	v_mul_f32_e32 v120, v102, v120
	v_mov_b32_e32 v102, v111
	v_mov_b32_e32 v114, v121
	v_mov_b32_e32 v110, v103
	v_pk_mul_f32 v[146:147], v[102:103], v[114:115]
	v_pk_mul_f32 v[102:103], v[110:111], v[114:115]
	v_pk_mul_f32 v[126:127], v[108:109], v[112:113]
	v_pk_mul_f32 v[112:113], v[100:101], v[112:113]
	v_mov_b32_e32 v121, v102
	v_mov_b32_e32 v145, v103
	v_pk_fma_f32 v[108:109], v[108:109], v[118:119], v[112:113] neg_lo:[0,0,1] neg_hi:[0,0,1]
	v_pk_fma_f32 v[100:101], v[100:101], v[118:119], v[126:127]
	v_pk_add_f32 v[102:103], v[120:121], v[144:145]
	s_nop 0
	v_mov_b32_e32 v141, v146
	v_mov_b32_e32 v143, v147
	v_pk_add_f32 v[112:113], v[140:141], v[142:143] neg_lo:[0,1] neg_hi:[0,1]
	s_waitcnt vmcnt(0)
	v_pk_mul_f32 v[110:111], v[104:105], v[232:233]
	v_pk_mul_f32 v[114:115], v[96:97], v[232:233]
	v_mul_f32_e32 v232, v106, v230
	v_mul_f32_e32 v126, v98, v234
	v_mul_f32_e32 v140, v106, v234
	v_mul_f32_e32 v230, v98, v230
	v_mov_b32_e32 v98, v107
	v_mov_b32_e32 v234, v231
	v_pk_mul_f32 v[142:143], v[98:99], v[234:235]
	v_mov_b32_e32 v106, v99
	v_mov_b32_e32 v233, v142
	v_mov_b32_e32 v127, v143
	v_pk_mul_f32 v[98:99], v[106:107], v[234:235]
	v_pk_fma_f32 v[104:105], v[104:105], v[228:229], v[114:115] neg_lo:[0,0,1] neg_hi:[0,0,1]
	v_pk_add_f32 v[114:115], v[232:233], v[126:127] neg_lo:[0,1] neg_hi:[0,1]
	v_mov_b32_e32 v231, v98
	v_mov_b32_e32 v141, v99
	v_pk_fma_f32 v[96:97], v[96:97], v[228:229], v[110:111]
	v_pk_add_f32 v[98:99], v[230:231], v[140:141]
	v_mov_b32_e32 v106, v114
	v_mov_b32_e32 v107, v115
	v_mov_b32_e32 v110, v112
	v_mov_b32_e32 v111, v113

.LBB0_564:
	s_andn2_saveexec_b64 s[30:31], s[30:31]
	s_cbranch_execz .LBB0_584
	s_and_saveexec_b64 vcc, s[48:49]
	s_cbranch_execz .LBB0_567
	v_or_b32_e32 v96, v181, v100
	v_lshlrev_b32_e32 v96, 7, v96
	v_mov_b32_e32 v97, v177
	v_lshl_add_u64 v[106:107], v[138:139], 0, v[96:97]
	v_lshl_add_u64 v[108:109], v[136:137], 0, v[96:97]
	global_load_dwordx4 v[102:105], v[106:107], off
	global_load_dwordx4 v[96:99], v[108:109], off
	global_load_dwordx4 v[228:231], v[106:107], off offset:64
	global_load_dwordx4 v[232:235], v[108:109], off offset:64
	s_waitcnt vmcnt(3)
	v_mul_f32_e32 v112, v94, v104
	s_waitcnt vmcnt(2)
	v_mul_f32_e32 v114, v86, v98
	v_mul_f32_e32 v116, v94, v98
	v_mul_f32_e32 v104, v86, v104
	v_mov_b32_e32 v86, v95
	v_mov_b32_e32 v98, v105
	v_mov_b32_e32 v94, v87
	v_pk_mul_f32 v[118:119], v[86:87], v[98:99]
	v_pk_mul_f32 v[86:87], v[94:95], v[98:99]
	v_pk_mul_f32 v[110:111], v[92:93], v[96:97]
	v_pk_mul_f32 v[96:97], v[84:85], v[96:97]
	v_mov_b32_e32 v105, v86
	v_mov_b32_e32 v117, v87
	v_pk_fma_f32 v[92:93], v[92:93], v[102:103], v[96:97] neg_lo:[0,0,1] neg_hi:[0,0,1]
	v_pk_fma_f32 v[84:85], v[84:85], v[102:103], v[110:111]
	v_pk_add_f32 v[86:87], v[104:105], v[116:117]
	s_nop 0
	v_mov_b32_e32 v113, v118
	v_mov_b32_e32 v115, v119
	v_pk_add_f32 v[96:97], v[112:113], v[114:115] neg_lo:[0,1] neg_hi:[0,1]
	s_waitcnt vmcnt(0)
	v_pk_mul_f32 v[94:95], v[88:89], v[232:233]
	v_pk_mul_f32 v[98:99], v[80:81], v[232:233]
	v_mul_f32_e32 v232, v90, v230
	v_mul_f32_e32 v110, v82, v234
	v_mul_f32_e32 v112, v90, v234
	v_mul_f32_e32 v230, v82, v230
	v_mov_b32_e32 v82, v91
	v_mov_b32_e32 v234, v231
	v_pk_mul_f32 v[114:115], v[82:83], v[234:235]
	v_mov_b32_e32 v90, v83
	v_mov_b32_e32 v233, v114
	v_mov_b32_e32 v111, v115
	v_pk_mul_f32 v[82:83], v[90:91], v[234:235]
	v_pk_fma_f32 v[88:89], v[88:89], v[228:229], v[98:99] neg_lo:[0,0,1] neg_hi:[0,0,1]
	v_pk_add_f32 v[98:99], v[232:233], v[110:111] neg_lo:[0,1] neg_hi:[0,1]
	v_mov_b32_e32 v231, v82
	v_mov_b32_e32 v113, v83
	v_pk_fma_f32 v[80:81], v[80:81], v[228:229], v[94:95]
	v_pk_add_f32 v[82:83], v[230:231], v[112:113]
	v_mov_b32_e32 v90, v98
	v_mov_b32_e32 v91, v99
	v_mov_b32_e32 v94, v96
	v_mov_b32_e32 v95, v97

.LBB0_600:
	s_andn2_saveexec_b64 s[30:31], s[30:31]
	s_cbranch_execz .LBB0_620
	s_and_saveexec_b64 vcc, s[48:49]
	s_cbranch_execz .LBB0_603
	v_or_b32_e32 v80, v181, v84
	v_lshlrev_b32_e32 v80, 7, v80
	v_mov_b32_e32 v81, v177
	v_lshl_add_u64 v[90:91], v[138:139], 0, v[80:81]
	v_lshl_add_u64 v[92:93], v[136:137], 0, v[80:81]
	global_load_dwordx4 v[86:89], v[90:91], off
	global_load_dwordx4 v[80:83], v[92:93], off
	global_load_dwordx4 v[228:231], v[90:91], off offset:64
	global_load_dwordx4 v[232:235], v[92:93], off offset:64
	s_waitcnt vmcnt(3)
	v_mul_f32_e32 v96, v78, v88
	s_waitcnt vmcnt(2)
	v_mul_f32_e32 v98, v70, v82
	v_mul_f32_e32 v100, v78, v82
	v_mul_f32_e32 v88, v70, v88
	v_mov_b32_e32 v70, v79
	v_mov_b32_e32 v82, v89
	v_mov_b32_e32 v78, v71
	v_pk_mul_f32 v[102:103], v[70:71], v[82:83]
	v_pk_mul_f32 v[70:71], v[78:79], v[82:83]
	v_pk_mul_f32 v[94:95], v[76:77], v[80:81]
	v_pk_mul_f32 v[80:81], v[68:69], v[80:81]
	v_mov_b32_e32 v89, v70
	v_mov_b32_e32 v101, v71
	v_pk_fma_f32 v[76:77], v[76:77], v[86:87], v[80:81] neg_lo:[0,0,1] neg_hi:[0,0,1]
	v_pk_fma_f32 v[68:69], v[68:69], v[86:87], v[94:95]
	v_pk_add_f32 v[70:71], v[88:89], v[100:101]
	s_nop 0
	v_mov_b32_e32 v97, v102
	v_mov_b32_e32 v99, v103
	v_pk_add_f32 v[80:81], v[96:97], v[98:99] neg_lo:[0,1] neg_hi:[0,1]
	s_waitcnt vmcnt(0)
	v_pk_mul_f32 v[78:79], v[72:73], v[232:233]
	v_pk_mul_f32 v[82:83], v[64:65], v[232:233]
	v_mul_f32_e32 v232, v74, v230
	v_mul_f32_e32 v94, v66, v234
	v_mul_f32_e32 v96, v74, v234
	v_mul_f32_e32 v230, v66, v230
	v_mov_b32_e32 v66, v75
	v_mov_b32_e32 v234, v231
	v_pk_mul_f32 v[98:99], v[66:67], v[234:235]
	v_mov_b32_e32 v74, v67
	v_mov_b32_e32 v233, v98
	v_mov_b32_e32 v95, v99
	v_pk_mul_f32 v[66:67], v[74:75], v[234:235]
	v_pk_fma_f32 v[72:73], v[72:73], v[228:229], v[82:83] neg_lo:[0,0,1] neg_hi:[0,0,1]
	v_pk_add_f32 v[82:83], v[232:233], v[94:95] neg_lo:[0,1] neg_hi:[0,1]
	v_mov_b32_e32 v231, v66
	v_mov_b32_e32 v97, v67
	v_pk_fma_f32 v[64:65], v[64:65], v[228:229], v[78:79]
	v_pk_add_f32 v[66:67], v[230:231], v[96:97]
	v_mov_b32_e32 v74, v82
	v_mov_b32_e32 v75, v83
	v_mov_b32_e32 v78, v80
	v_mov_b32_e32 v79, v81

.LBB0_636:
	s_andn2_saveexec_b64 s[30:31], s[30:31]
	s_cbranch_execz .LBB0_656
	s_and_saveexec_b64 vcc, s[48:49]
	s_cbranch_execz .LBB0_639
	v_or_b32_e32 v64, v181, v68
	v_lshlrev_b32_e32 v64, 7, v64
	v_mov_b32_e32 v65, v177
	v_lshl_add_u64 v[74:75], v[138:139], 0, v[64:65]
	v_lshl_add_u64 v[76:77], v[136:137], 0, v[64:65]
	global_load_dwordx4 v[70:73], v[74:75], off
	global_load_dwordx4 v[64:67], v[76:77], off
	global_load_dwordx4 v[228:231], v[74:75], off offset:64
	global_load_dwordx4 v[232:235], v[76:77], off offset:64
	s_waitcnt vmcnt(3)
	v_mul_f32_e32 v80, v62, v72
	s_waitcnt vmcnt(2)
	v_mul_f32_e32 v82, v54, v66
	v_mul_f32_e32 v84, v62, v66
	v_mul_f32_e32 v72, v54, v72
	v_mov_b32_e32 v54, v63
	v_mov_b32_e32 v66, v73
	v_mov_b32_e32 v62, v55
	v_pk_mul_f32 v[86:87], v[54:55], v[66:67]
	v_pk_mul_f32 v[54:55], v[62:63], v[66:67]
	v_pk_mul_f32 v[78:79], v[60:61], v[64:65]
	v_pk_mul_f32 v[64:65], v[52:53], v[64:65]
	v_mov_b32_e32 v73, v54
	v_mov_b32_e32 v85, v55
	v_pk_fma_f32 v[60:61], v[60:61], v[70:71], v[64:65] neg_lo:[0,0,1] neg_hi:[0,0,1]
	v_pk_fma_f32 v[52:53], v[52:53], v[70:71], v[78:79]
	v_pk_add_f32 v[54:55], v[72:73], v[84:85]
	s_nop 0
	v_mov_b32_e32 v81, v86
	v_mov_b32_e32 v83, v87
	v_pk_add_f32 v[64:65], v[80:81], v[82:83] neg_lo:[0,1] neg_hi:[0,1]
	s_waitcnt vmcnt(0)
	v_pk_mul_f32 v[62:63], v[56:57], v[232:233]
	v_pk_mul_f32 v[66:67], v[48:49], v[232:233]
	v_mul_f32_e32 v232, v58, v230
	v_mul_f32_e32 v78, v50, v234
	v_mul_f32_e32 v80, v58, v234
	v_mul_f32_e32 v230, v50, v230
	v_mov_b32_e32 v50, v59
	v_mov_b32_e32 v234, v231
	v_pk_mul_f32 v[82:83], v[50:51], v[234:235]
	v_mov_b32_e32 v58, v51
	v_mov_b32_e32 v233, v82
	v_mov_b32_e32 v79, v83
	v_pk_mul_f32 v[50:51], v[58:59], v[234:235]
	v_pk_fma_f32 v[56:57], v[56:57], v[228:229], v[66:67] neg_lo:[0,0,1] neg_hi:[0,0,1]
	v_pk_add_f32 v[66:67], v[232:233], v[78:79] neg_lo:[0,1] neg_hi:[0,1]
	v_mov_b32_e32 v231, v50
	v_mov_b32_e32 v81, v51
	v_pk_fma_f32 v[48:49], v[48:49], v[228:229], v[62:63]
	v_pk_add_f32 v[50:51], v[230:231], v[80:81]
	v_mov_b32_e32 v58, v66
	v_mov_b32_e32 v59, v67
	v_mov_b32_e32 v62, v64
	v_mov_b32_e32 v63, v65

.LBB0_672:
	s_andn2_saveexec_b64 s[30:31], s[30:31]
	s_cbranch_execz .LBB0_692
	s_and_saveexec_b64 vcc, s[48:49]
	s_cbranch_execz .LBB0_675
	v_or_b32_e32 v48, v181, v52
	v_lshlrev_b32_e32 v48, 7, v48
	v_mov_b32_e32 v49, v177
	v_lshl_add_u64 v[58:59], v[138:139], 0, v[48:49]
	v_lshl_add_u64 v[60:61], v[136:137], 0, v[48:49]
	global_load_dwordx4 v[54:57], v[58:59], off
	global_load_dwordx4 v[48:51], v[60:61], off
	global_load_dwordx4 v[228:231], v[58:59], off offset:64
	global_load_dwordx4 v[232:235], v[60:61], off offset:64
	s_waitcnt vmcnt(3)
	v_mul_f32_e32 v64, v46, v56
	s_waitcnt vmcnt(2)
	v_mul_f32_e32 v66, v38, v50
	v_mul_f32_e32 v68, v46, v50
	v_mul_f32_e32 v56, v38, v56
	v_mov_b32_e32 v38, v47
	v_mov_b32_e32 v50, v57
	v_mov_b32_e32 v46, v39
	v_pk_mul_f32 v[70:71], v[38:39], v[50:51]
	v_pk_mul_f32 v[38:39], v[46:47], v[50:51]
	v_pk_mul_f32 v[62:63], v[44:45], v[48:49]
	v_pk_mul_f32 v[48:49], v[36:37], v[48:49]
	v_mov_b32_e32 v57, v38
	v_mov_b32_e32 v69, v39
	v_pk_fma_f32 v[44:45], v[44:45], v[54:55], v[48:49] neg_lo:[0,0,1] neg_hi:[0,0,1]
	v_pk_fma_f32 v[36:37], v[36:37], v[54:55], v[62:63]
	v_pk_add_f32 v[38:39], v[56:57], v[68:69]
	s_nop 0
	v_mov_b32_e32 v65, v70
	v_mov_b32_e32 v67, v71
	v_pk_add_f32 v[48:49], v[64:65], v[66:67] neg_lo:[0,1] neg_hi:[0,1]
	s_waitcnt vmcnt(0)
	v_pk_mul_f32 v[46:47], v[40:41], v[232:233]
	v_pk_mul_f32 v[50:51], v[32:33], v[232:233]
	v_mul_f32_e32 v232, v42, v230
	v_mul_f32_e32 v62, v34, v234
	v_mul_f32_e32 v64, v42, v234
	v_mul_f32_e32 v230, v34, v230
	v_mov_b32_e32 v34, v43
	v_mov_b32_e32 v234, v231
	v_pk_mul_f32 v[66:67], v[34:35], v[234:235]
	v_mov_b32_e32 v42, v35
	v_mov_b32_e32 v233, v66
	v_mov_b32_e32 v63, v67
	v_pk_mul_f32 v[34:35], v[42:43], v[234:235]
	v_pk_fma_f32 v[40:41], v[40:41], v[228:229], v[50:51] neg_lo:[0,0,1] neg_hi:[0,0,1]
	v_pk_add_f32 v[50:51], v[232:233], v[62:63] neg_lo:[0,1] neg_hi:[0,1]
	v_mov_b32_e32 v231, v34
	v_mov_b32_e32 v65, v35
	v_pk_fma_f32 v[32:33], v[32:33], v[228:229], v[46:47]
	v_pk_add_f32 v[34:35], v[230:231], v[64:65]
	v_mov_b32_e32 v42, v50
	v_mov_b32_e32 v43, v51
	v_mov_b32_e32 v46, v48
	v_mov_b32_e32 v47, v49

.LBB0_708:
	s_andn2_saveexec_b64 s[30:31], s[30:31]
	s_cbranch_execz .LBB0_728
	s_and_saveexec_b64 vcc, s[48:49]
	s_cbranch_execz .LBB0_711
	v_or_b32_e32 v32, v181, v36
	v_lshlrev_b32_e32 v32, 7, v32
	v_mov_b32_e32 v33, v177
	v_lshl_add_u64 v[42:43], v[138:139], 0, v[32:33]
	v_lshl_add_u64 v[44:45], v[136:137], 0, v[32:33]
	global_load_dwordx4 v[38:41], v[42:43], off
	global_load_dwordx4 v[32:35], v[44:45], off
	global_load_dwordx4 v[228:231], v[42:43], off offset:64
	global_load_dwordx4 v[232:235], v[44:45], off offset:64
	s_waitcnt vmcnt(3)
	v_mul_f32_e32 v48, v30, v40
	s_waitcnt vmcnt(2)
	v_mul_f32_e32 v50, v22, v34
	v_mul_f32_e32 v52, v30, v34
	v_mul_f32_e32 v40, v22, v40
	v_mov_b32_e32 v22, v31
	v_mov_b32_e32 v34, v41
	v_mov_b32_e32 v30, v23
	v_pk_mul_f32 v[54:55], v[22:23], v[34:35]
	v_pk_mul_f32 v[22:23], v[30:31], v[34:35]
	v_pk_mul_f32 v[46:47], v[28:29], v[32:33]
	v_pk_mul_f32 v[32:33], v[20:21], v[32:33]
	v_mov_b32_e32 v41, v22
	v_mov_b32_e32 v53, v23
	v_pk_fma_f32 v[28:29], v[28:29], v[38:39], v[32:33] neg_lo:[0,0,1] neg_hi:[0,0,1]
	v_pk_fma_f32 v[20:21], v[20:21], v[38:39], v[46:47]
	v_pk_add_f32 v[22:23], v[40:41], v[52:53]
	s_nop 0
	v_mov_b32_e32 v49, v54
	v_mov_b32_e32 v51, v55
	v_pk_add_f32 v[32:33], v[48:49], v[50:51] neg_lo:[0,1] neg_hi:[0,1]
	s_waitcnt vmcnt(0)
	v_pk_mul_f32 v[30:31], v[24:25], v[232:233]
	v_pk_mul_f32 v[34:35], v[16:17], v[232:233]
	v_mul_f32_e32 v232, v26, v230
	v_mul_f32_e32 v46, v18, v234
	v_mul_f32_e32 v48, v26, v234
	v_mul_f32_e32 v230, v18, v230
	v_mov_b32_e32 v18, v27
	v_mov_b32_e32 v234, v231
	v_pk_mul_f32 v[50:51], v[18:19], v[234:235]
	v_mov_b32_e32 v26, v19
	v_mov_b32_e32 v233, v50
	v_mov_b32_e32 v47, v51
	v_pk_mul_f32 v[18:19], v[26:27], v[234:235]
	v_pk_fma_f32 v[24:25], v[24:25], v[228:229], v[34:35] neg_lo:[0,0,1] neg_hi:[0,0,1]
	v_pk_add_f32 v[34:35], v[232:233], v[46:47] neg_lo:[0,1] neg_hi:[0,1]
	v_mov_b32_e32 v231, v18
	v_mov_b32_e32 v49, v19
	v_pk_fma_f32 v[16:17], v[16:17], v[228:229], v[30:31]
	v_pk_add_f32 v[18:19], v[230:231], v[48:49]
	v_mov_b32_e32 v26, v34
	v_mov_b32_e32 v27, v35
	v_mov_b32_e32 v30, v32
	v_mov_b32_e32 v31, v33

.LBB0_744:
	s_andn2_saveexec_b64 s[50:51], s[30:31]
	s_cbranch_execz .LBB0_764
	s_and_saveexec_b64 s[30:31], s[48:49]
	s_cbranch_execz .LBB0_747
	v_or_b32_e32 v16, v181, v22
	v_lshlrev_b32_e32 v176, 7, v16
	v_lshl_add_u64 v[28:29], v[138:139], 0, v[176:177]
	v_lshl_add_u64 v[30:31], v[136:137], 0, v[176:177]
	global_load_dwordx4 v[18:21], v[28:29], off
	global_load_dwordx4 v[24:27], v[30:31], off
	global_load_dwordx4 v[228:231], v[28:29], off offset:64
	global_load_dwordx4 v[232:235], v[30:31], off offset:64
	s_waitcnt vmcnt(2)
	v_pk_mul_f32 v[32:33], v[12:13], v[24:25]
	v_pk_mul_f32 v[16:17], v[4:5], v[24:25]
	v_mul_f32_e32 v24, v14, v20
	v_mul_f32_e32 v34, v6, v26
	v_mul_f32_e32 v36, v14, v26
	v_mul_f32_e32 v20, v6, v20
	v_mov_b32_e32 v6, v15
	v_mov_b32_e32 v26, v21
	v_mov_b32_e32 v14, v7
	v_pk_mul_f32 v[38:39], v[6:7], v[26:27]
	v_pk_mul_f32 v[6:7], v[14:15], v[26:27]
	v_mov_b32_e32 v25, v38
	v_mov_b32_e32 v35, v39
	v_mov_b32_e32 v21, v6
	v_mov_b32_e32 v37, v7
	v_pk_fma_f32 v[12:13], v[12:13], v[18:19], v[16:17] neg_lo:[0,0,1] neg_hi:[0,0,1]
	v_pk_add_f32 v[16:17], v[24:25], v[34:35] neg_lo:[0,1] neg_hi:[0,1]
	v_pk_fma_f32 v[4:5], v[4:5], v[18:19], v[32:33]
	v_pk_add_f32 v[6:7], v[20:21], v[36:37]
	s_waitcnt vmcnt(1)
	v_mul_f32_e32 v28, v10, v230
	s_waitcnt vmcnt(0)
	v_mul_f32_e32 v30, v2, v234
	v_mul_f32_e32 v32, v10, v234
	v_mul_f32_e32 v230, v2, v230
	v_mov_b32_e32 v2, v11
	v_mov_b32_e32 v234, v231
	v_pk_mul_f32 v[34:35], v[2:3], v[234:235]
	v_mov_b32_e32 v10, v3
	v_pk_mul_f32 v[14:15], v[8:9], v[232:233]
	v_pk_mul_f32 v[232:233], v[0:1], v[232:233]
	v_mov_b32_e32 v29, v34
	v_mov_b32_e32 v31, v35
	v_pk_mul_f32 v[2:3], v[10:11], v[234:235]
	v_pk_fma_f32 v[8:9], v[8:9], v[228:229], v[232:233] neg_lo:[0,0,1] neg_hi:[0,0,1]
	v_pk_add_f32 v[232:233], v[28:29], v[30:31] neg_lo:[0,1] neg_hi:[0,1]
	v_mov_b32_e32 v231, v2
	v_mov_b32_e32 v33, v3
	v_pk_fma_f32 v[0:1], v[0:1], v[228:229], v[14:15]
	v_pk_add_f32 v[2:3], v[230:231], v[32:33]
	v_mov_b32_e32 v10, v232
	v_mov_b32_e32 v11, v233
	v_mov_b32_e32 v14, v16
	v_mov_b32_e32 v15, v17
